# attention: one static s_setprio 1 for waves 4-7 at phase entry (reset at phase end), entry code padded to 64 B; on top of v35
# baseline (speedup 1.0000x reference)
; __device__ __forceinline__ void attn_phase(const Ctx& c, int j, char* lds) {
;     const att::bf16* P = (const att::bf16*)(c.ws + WS_P); unsigned short* O = (unsigned short*)(c.ws + WS_A);
;     float* PART = (float*)(c.ws + WS_X);
;     unsigned* CNT = (unsigned*)(c.ws + WS_CTL) + 8192 + j * 64;
;     const float* QNW = c.attn_q_norm + j * 128; const float2* RTAB = (const float2*)(c.ws + WS_ROPE);
;     for (int u = blockIdx.x; u < 1024 + 224; u += c.G) {
;         if (u < 1024) {
;             const int r = u >> 8, w = u & 255, x = w & 7, slot = w >> 3, pair = r * 8 + x;
.LBB0_267:
	s_cmp_lt_i32 s74, 4
	s_cselect_b64 s[0:1], -1, 0
	s_cmp_gt_i32 s75, 3
	s_cselect_b64 s[2:3], -1, 0
	s_and_b64 s[0:1], s[0:1], s[2:3]
	s_andn2_b64 vcc, exec, s[0:1]
	v_writelane_b32 v254, s63, 29
	s_cbranch_vccnz .LBB0_377
	v_readfirstlane_b32 s98, v200
	s_nop 3
	s_lshr_b32 s98, s98, 6
	s_cmp_ge_u32 s98, 4
	s_cbranch_scc0 .Lattn_prio_a
	s_setprio 1
.Lattn_prio_a:
	s_nop 0
	s_nop 0
	s_nop 0
	s_nop 0
	s_nop 0
	s_nop 0
	s_nop 0
	s_nop 0
	s_nop 0
	s_nop 0
	v_mov_b32_e32 v0, v200
	s_cmpk_gt_i32 s76, 0x4df
	s_cbranch_scc1 .LBB0_323
	s_add_u32 s6, s72, 0x6300000
	s_addc_u32 s7, s73, 0
	s_add_u32 s24, s72, 0x2200000
	s_addc_u32 s25, s73, 0
	s_add_u32 s31, s72, 0x12500000
	s_addc_u32 s38, s73, 0
	s_add_u32 s26, s72, 0x8000
	s_addc_u32 s27, s73, 0
	s_add_u32 s28, s72, 0x80000
	s_addc_u32 s29, s73, 0
	s_add_u32 s39, s72, 0x6301000
	v_mbcnt_lo_u32_b32 v0, -1, 0
	s_addc_u32 s40, s73, 0
	v_mbcnt_hi_u32_b32 v186, -1, v0
	s_add_u32 s41, s72, 0x65a1800
	v_and_b32_e32 v0, 64, v186
	s_addc_u32 s42, s73, 0
	s_movk_i32 s43, 0x4000
	s_movk_i32 s44, 0x3000
	s_mov_b32 s9, 0
	v_mov_b32_e32 v177, 0
	v_mov_b32_e32 v184, 0x358637bd
	s_mov_b32 s45, 0xf800000
	v_mov_b32_e32 v185, 0x260
	s_movk_i32 s46, 0x1800
	s_mov_b32 s47, 0x10000
	s_mov_b32 s48, 0x42b504f3
	s_mov_b32 s49, 0x60000
	s_mov_b32 s30, 0x3e0293ee
	s_movk_i32 s50, 0x2000
	s_mov_b32 s51, 0x8000
	s_mov_b32 s77, 0xc000
	s_mov_b32 s78, 0x14000
	s_mov_b32 s79, 0x18000
	s_movk_i32 s80, 0x7fff
	s_mov_b32 s81, 0x7060302
	s_add_i32 s82, 0, 0x10800
	v_xor_b32_e32 v187, 32, v186
	v_add_u32_e32 v188, 64, v0
	v_mov_b32_e32 v189, 0x2d000
	v_mov_b32_e32 v190, 0xf149f2ca
	v_mov_b32_e32 v191, 0x3e0293ee
	s_mov_b32 s83, s76
	s_mov_b32 s84, s76
	s_mov_b32 s85, s76
	s_branch .LBB0_272

; __device__ __forceinline__ void xcd_barrier(const XcdBarrier& b) {
;     ...
;             asm volatile("s_waitcnt vmcnt(0)" ::: "memory");
;         }
;     }
;     __syncthreads();
.LBB0_376:
	s_or_b64 exec, exec, s[2:3]
	s_waitcnt lgkmcnt(0)
	s_barrier
	s_setprio 0
	s_nop 0
	s_nop 0
	s_nop 0
	s_nop 0
	s_nop 0
	s_nop 0
	s_nop 0
	s_nop 0
	s_nop 0
	s_nop 0
	s_nop 0
	s_nop 0
	s_nop 0

; __device__ __forceinline__ void attn_phase(const Ctx& c, int j, char* lds) {
;     const att::bf16* P = (const att::bf16*)(c.ws + WS_P); unsigned short* O = (unsigned short*)(c.ws + WS_A);
;     float* PART = (float*)(c.ws + WS_X);
;     unsigned* CNT = (unsigned*)(c.ws + WS_CTL) + 8192 + j * 64;
;     const float* QNW = c.attn_q_norm + j * 128; const float2* RTAB = (const float2*)(c.ws + WS_ROPE);
;     for (int u = blockIdx.x; u < 1024 + 224; u += c.G) {
;         if (u < 1024) {
;             const int r = u >> 8, w = u & 255, x = w & 7, slot = w >> 3, pair = r * 8 + x;
.LBB0_1231:
	s_cmp_lt_i32 s74, 20
	s_cselect_b64 s[0:1], -1, 0
	s_cmp_gt_i32 s75, 19
	v_writelane_b32 v254, s68, 30
	s_cselect_b64 s[2:3], -1, 0
	s_and_b64 s[0:1], s[0:1], s[2:3]
	v_writelane_b32 v254, s69, 31
	v_writelane_b32 v254, s70, 32
	v_writelane_b32 v254, s71, 33
	v_writelane_b32 v254, s72, 34
	v_writelane_b32 v254, s73, 35
	s_andn2_b64 vcc, exec, s[0:1]
	v_writelane_b32 v254, s74, 36
	v_writelane_b32 v254, s75, 37
	s_cbranch_vccnz .LBB0_1341
	v_readfirstlane_b32 s98, v200
	s_nop 3
	s_lshr_b32 s98, s98, 6
	s_cmp_ge_u32 s98, 4
	s_cbranch_scc0 .Lattn_prio_b
	s_setprio 1
.Lattn_prio_b:
	s_nop 0
	s_nop 0
	s_nop 0
	s_nop 0
	s_nop 0
	s_nop 0
	s_nop 0
	s_nop 0
	s_nop 0
	s_nop 0
	v_mov_b32_e32 v0, v200
	s_cmpk_gt_i32 s76, 0x4df
	s_cbranch_scc1 .LBB0_1287
	s_add_u32 s6, s72, 0x6300000
	s_addc_u32 s7, s73, 0
	s_add_u32 s24, s72, 0x2200000
	s_addc_u32 s25, s73, 0
	s_add_u32 s31, s72, 0x12500000
	s_addc_u32 s40, s73, 0
	s_add_u32 s0, s72, 0x8100
	s_addc_u32 s1, s73, 0
	s_add_u32 s28, s72, 0x80000
	s_addc_u32 s29, s73, 0
	s_add_u32 s41, s72, 0x6301000
	v_mbcnt_lo_u32_b32 v0, -1, 0
	s_addc_u32 s42, s73, 0
	s_waitcnt vmcnt(0)
	v_mbcnt_hi_u32_b32 v186, -1, v0
	s_add_u32 s43, s72, 0x65a1800
	v_and_b32_e32 v0, 64, v186
	v_writelane_b32 v254, s0, 40
	s_addc_u32 s44, s73, 0
	s_movk_i32 s46, 0x3000
	s_mov_b32 s65, 0
	v_mov_b32_e32 v177, 0
	v_mov_b32_e32 v184, 0x358637bd
	s_mov_b32 s47, 0xf800000
	v_mov_b32_e32 v185, 0x260
	s_movk_i32 s48, 0x1800
	s_mov_b32 s49, 0x10000
	s_mov_b32 s50, 0x42b504f3
	s_mov_b32 s51, 0x60000
	s_mov_b32 s30, 0x3e0293ee
	s_movk_i32 s52, 0x2000
	s_mov_b32 s53, 0x8000
	s_mov_b32 s54, 0xc000
	s_mov_b32 s55, 0x14000
	s_mov_b32 s60, 0x18000
	s_movk_i32 s61, 0x7fff
	s_mov_b32 s59, 0x7060302
	s_mov_b32 s62, 0x120000
	s_mov_b64 s[34:35], 0x180000
	s_movk_i32 s96, 0x2200
	s_add_i32 s97, 0, 0x10800
	v_xor_b32_e32 v187, 32, v186
	v_add_u32_e32 v188, 64, v0
	v_mov_b32_e32 v189, 0x2d000
	v_mov_b32_e32 v190, 0xf149f2ca
	v_mov_b32_e32 v191, 0x3e0293ee
	s_mov_b32 s26, s76
	s_mov_b32 s27, s76
	s_mov_b32 s45, s76
	v_writelane_b32 v254, s1, 41
	s_branch .LBB0_1236
